# grid barrier: non-last arrivers poll the global generation word directly, per-XCD relay add removed
# baseline (speedup 1.0000x reference)
.LBB0_131:
	s_or_b64 exec, exec, s[8:9]
	v_cvt_f32_u32_e32 v5, v3
	s_waitcnt vmcnt(0)
	v_readfirstlane_b32 s3, v4
	v_sub_u32_e32 v4, 0, v3
	v_rcp_iflag_f32_e32 v5, v5
	v_add_u32_e32 v6, s3, v2
	v_mul_f32_e32 v5, 0x4f7ffffe, v5
	v_cvt_u32_f32_e32 v5, v5
	v_mul_lo_u32 v2, v4, v5
	v_mul_hi_u32 v2, v5, v2
	v_add_u32_e32 v2, v5, v2
	v_mul_hi_u32 v2, v6, v2
	v_mul_lo_u32 v4, v2, v3
	v_sub_u32_e32 v4, v6, v4
	v_add_u32_e32 v5, 1, v2
	v_cmp_ge_u32_e32 vcc, v4, v3
	s_nop 1
	v_cndmask_b32_e32 v2, v2, v5, vcc
	v_sub_u32_e32 v5, v4, v3
	v_cndmask_b32_e32 v4, v4, v5, vcc
	v_add_u32_e32 v5, 1, v2
	v_cmp_ge_u32_e32 vcc, v4, v3
	v_add_u32_e32 v4, 1, v6
	s_nop 0
	v_cndmask_b32_e32 v2, v2, v5, vcc
	v_mul_lo_u32 v5, v3, v2
	v_add_u32_e32 v3, v5, v3
	v_cmp_ne_u32_e32 vcc, v4, v3
	s_and_saveexec_b64 s[6:7], vcc
	s_xor_b64 s[6:7], exec, s[6:7]
	s_cbranch_execz .LBB0_145
	s_waitcnt lgkmcnt(0)
	v_mov_b32_e32 v1, 0x3100
	global_load_dword v1, v1, s[88:89] offset:1024 sc1
	s_add_u32 s10, s88, 0x3500
	s_addc_u32 s11, s89, 0
	s_waitcnt vmcnt(0)
	v_cmp_eq_u32_e32 vcc, v1, v2
	s_and_saveexec_b64 s[8:9], vcc
	s_cbranch_execz .LBB0_144
	s_mov_b32 s3, 1
	s_mov_b64 s[12:13], 0
	v_mov_b32_e32 v1, 0
	s_branch .LBB0_135

.LBB0_162:
	s_or_b64 exec, exec, s[6:7]
	s_mov_b64 s[6:7], exec
	v_mbcnt_lo_u32_b32 v1, s6, 0
	v_mbcnt_hi_u32_b32 v1, s7, v1
	v_cmp_eq_u32_e32 vcc, 0, v1
	s_waitcnt vmcnt(0)
	buffer_inv sc1
	s_and_saveexec_b64 s[8:9], vcc
	s_cbranch_execz .LBB0_164
	s_bcnt1_i32_b64 s3, s[6:7]
	v_mov_b32_e32 v1, 0x2000
	v_mov_b32_e32 v2, s3
.LBB0_164:
	s_or_b64 exec, exec, s[8:9]
	s_waitcnt vmcnt(0)

.LBB0_192:
	s_or_b64 exec, exec, s[8:9]
	v_cvt_f32_u32_e32 v6, v4
	s_waitcnt vmcnt(0)
	v_readfirstlane_b32 s3, v5
	v_sub_u32_e32 v5, 0, v4
	v_rcp_iflag_f32_e32 v6, v6
	v_add_u32_e32 v7, s3, v3
	v_mul_f32_e32 v6, 0x4f7ffffe, v6
	v_cvt_u32_f32_e32 v6, v6
	v_mul_lo_u32 v3, v5, v6
	v_mul_hi_u32 v3, v6, v3
	v_add_u32_e32 v3, v6, v3
	v_mul_hi_u32 v3, v7, v3
	v_mul_lo_u32 v5, v3, v4
	v_sub_u32_e32 v5, v7, v5
	v_add_u32_e32 v6, 1, v3
	v_cmp_ge_u32_e32 vcc, v5, v4
	s_nop 1
	v_cndmask_b32_e32 v3, v3, v6, vcc
	v_sub_u32_e32 v6, v5, v4
	v_cndmask_b32_e32 v5, v5, v6, vcc
	v_add_u32_e32 v6, 1, v3
	v_cmp_ge_u32_e32 vcc, v5, v4
	v_add_u32_e32 v5, 1, v7
	s_nop 0
	v_cndmask_b32_e32 v3, v3, v6, vcc
	v_mul_lo_u32 v6, v4, v3
	v_add_u32_e32 v4, v6, v4
	v_cmp_ne_u32_e32 vcc, v5, v4
	s_and_saveexec_b64 s[6:7], vcc
	s_xor_b64 s[6:7], exec, s[6:7]
	s_cbranch_execz .LBB0_206
	s_waitcnt lgkmcnt(0)
	v_mov_b32_e32 v2, 0x3100
	global_load_dword v2, v2, s[88:89] offset:1024 sc1
	s_add_u32 s10, s88, 0x3500
	s_addc_u32 s11, s89, 0
	s_waitcnt vmcnt(0)
	v_cmp_eq_u32_e32 vcc, v2, v3
	s_and_saveexec_b64 s[8:9], vcc
	s_cbranch_execz .LBB0_205
	s_mov_b32 s3, 1
	s_mov_b64 s[12:13], 0
	v_mov_b32_e32 v2, 0
	s_branch .LBB0_196

.LBB0_223:
	s_or_b64 exec, exec, s[6:7]
	s_mov_b64 s[6:7], exec
	v_mbcnt_lo_u32_b32 v2, s6, 0
	v_mbcnt_hi_u32_b32 v2, s7, v2
	v_cmp_eq_u32_e32 vcc, 0, v2
	s_waitcnt vmcnt(0)
	buffer_inv sc1
	s_and_saveexec_b64 s[8:9], vcc
	s_cbranch_execz .LBB0_225
	s_bcnt1_i32_b64 s3, s[6:7]
	v_mov_b32_e32 v2, 0x2000
	v_mov_b32_e32 v3, s3
.LBB0_225:
	s_or_b64 exec, exec, s[8:9]
	s_waitcnt vmcnt(0)

.LBB0_445:
	s_or_b64 exec, exec, s[6:7]
	v_cvt_f32_u32_e32 v6, v4
	s_waitcnt vmcnt(0)
	v_readfirstlane_b32 s4, v5
	v_sub_u32_e32 v5, 0, v4
	v_rcp_iflag_f32_e32 v6, v6
	v_add_u32_e32 v7, s4, v3
	v_mul_f32_e32 v6, 0x4f7ffffe, v6
	v_cvt_u32_f32_e32 v6, v6
	v_mul_lo_u32 v3, v5, v6
	v_mul_hi_u32 v3, v6, v3
	v_add_u32_e32 v3, v6, v3
	v_mul_hi_u32 v3, v7, v3
	v_mul_lo_u32 v5, v3, v4
	v_sub_u32_e32 v5, v7, v5
	v_add_u32_e32 v6, 1, v3
	v_cmp_ge_u32_e32 vcc, v5, v4
	s_nop 1
	v_cndmask_b32_e32 v3, v3, v6, vcc
	v_sub_u32_e32 v6, v5, v4
	v_cndmask_b32_e32 v5, v5, v6, vcc
	v_add_u32_e32 v6, 1, v3
	v_cmp_ge_u32_e32 vcc, v5, v4
	v_add_u32_e32 v5, 1, v7
	s_nop 0
	v_cndmask_b32_e32 v3, v3, v6, vcc
	v_mul_lo_u32 v6, v4, v3
	v_add_u32_e32 v4, v6, v4
	v_cmp_ne_u32_e32 vcc, v5, v4
	s_and_saveexec_b64 s[4:5], vcc
	s_xor_b64 s[4:5], exec, s[4:5]
	s_cbranch_execz .LBB0_459
	s_waitcnt lgkmcnt(0)
	v_mov_b32_e32 v2, 0x3100
	global_load_dword v2, v2, s[88:89] offset:1024 sc1
	s_add_u32 s8, s88, 0x3500
	s_addc_u32 s9, s89, 0
	s_waitcnt vmcnt(0)
	v_cmp_eq_u32_e32 vcc, v2, v3
	s_and_saveexec_b64 s[6:7], vcc
	s_cbranch_execz .LBB0_458
	s_mov_b32 s20, 1
	s_mov_b64 s[10:11], 0
	v_mov_b32_e32 v2, 0
	s_branch .LBB0_449

.LBB0_476:
	s_or_b64 exec, exec, s[4:5]
	s_mov_b64 s[4:5], exec
	v_mbcnt_lo_u32_b32 v2, s4, 0
	v_mbcnt_hi_u32_b32 v2, s5, v2
	v_cmp_eq_u32_e32 vcc, 0, v2
	s_waitcnt vmcnt(0)
	buffer_inv sc1
	s_and_saveexec_b64 s[6:7], vcc
	s_cbranch_execz .LBB0_478
	s_bcnt1_i32_b64 s4, s[4:5]
	v_mov_b32_e32 v2, 0x2000
	v_mov_b32_e32 v3, s4
.LBB0_478:
	s_or_b64 exec, exec, s[6:7]
	s_waitcnt vmcnt(0)

.LBB0_563:
	s_or_b64 exec, exec, s[4:5]
	s_mov_b64 s[4:5], exec
	v_mbcnt_lo_u32_b32 v2, s4, 0
	v_mbcnt_hi_u32_b32 v2, s5, v2
	v_cmp_eq_u32_e32 vcc, 0, v2
	s_waitcnt vmcnt(0)
	buffer_inv sc1
	s_and_saveexec_b64 s[6:7], vcc
	s_cbranch_execz .LBB0_565
	s_bcnt1_i32_b64 s4, s[4:5]
	v_mov_b32_e32 v2, 0x2000
	v_mov_b32_e32 v3, s4
.LBB0_565:
	s_or_b64 exec, exec, s[6:7]
	s_waitcnt vmcnt(0)
